# GU K-loop: all 16 LDS-DMA loads use scalar-base addressing (vOff, s[base] [offset:128 with m0-128]); 16 v_lshl_add_u64 per iteration removed (on keep_v8)
# speedup vs baseline: 1.0069x; 1.0069x over previous
.LBB0_846:
	s_add_u32 s9, s96, 0xfffc0080
	s_addc_u32 s38, s97, -1
	s_add_i32 s78, 0, 0x10000
	s_cmp_eq_u32 s75, 12
	s_cselect_b32 vcc_hi, s25, s38
	s_cselect_b32 vcc_lo, s28, s9
	v_add_u32_e32 v148, s78, v145
	s_cselect_b32 s39, s23, s61
	s_cselect_b32 s38, s29, s53
	s_add_i32 s9, 0, 0x14000
	ds_read_b128 v[140:143], v148
	ds_read_b128 v[156:159], v148 offset:1024
	ds_read_b128 v[160:163], v148 offset:2048
	ds_read_b128 v[164:167], v148 offset:3072
	v_add_u32_e32 v148, s9, v145
	ds_read_b128 v[168:171], v148
	ds_read_b128 v[172:175], v148 offset:1024
	ds_read_b128 v[176:179], v148 offset:2048
	ds_read_b128 v[180:183], v148 offset:3072
	s_add_i32 m0, s46, 0xc000
	ds_read_b128 v[184:187], v147
	ds_read_b128 v[188:191], v147 offset:1024
	ds_read_b128 v[192:195], v147 offset:2048
	ds_read_b128 v[196:199], v147 offset:3072
	ds_read_b128 v[200:203], v147 offset:4096
	ds_read_b128 v[204:207], v147 offset:5120
	ds_read_b128 v[208:211], v147 offset:6144
	ds_read_b128 v[212:215], v147 offset:7168
	global_load_lds_dwordx4 v136, s[96:97]
	s_add_i32 m0, s46, 0xe000
	s_nop 0
	global_load_lds_dwordx4 v138, s[96:97]
	s_waitcnt vmcnt(8)
	s_waitcnt lgkmcnt(0)
	s_barrier
	s_setprio 1
	v_mfma_f32_16x16x32_bf16 v[126:129], v[140:143], v[184:187], v[126:129]
	v_mfma_f32_16x16x32_bf16 v[118:121], v[160:163], v[184:187], v[118:121]
	v_mfma_f32_16x16x32_bf16 v[110:113], v[140:143], v[192:195], v[110:113]
	v_mfma_f32_16x16x32_bf16 v[102:105], v[160:163], v[192:195], v[102:105]
	v_mfma_f32_16x16x32_bf16 v[94:97], v[140:143], v[200:203], v[94:97]
	v_mfma_f32_16x16x32_bf16 v[86:89], v[160:163], v[200:203], v[86:89]
	v_mfma_f32_16x16x32_bf16 v[78:81], v[140:143], v[208:211], v[78:81]
	v_mfma_f32_16x16x32_bf16 v[70:73], v[160:163], v[208:211], v[70:73]
	v_mfma_f32_16x16x32_bf16 v[126:129], v[156:159], v[188:191], v[126:129]
	v_mfma_f32_16x16x32_bf16 v[118:121], v[164:167], v[188:191], v[118:121]
	v_mfma_f32_16x16x32_bf16 v[110:113], v[156:159], v[196:199], v[110:113]
	v_mfma_f32_16x16x32_bf16 v[102:105], v[164:167], v[196:199], v[102:105]
	v_mfma_f32_16x16x32_bf16 v[94:97], v[156:159], v[204:207], v[94:97]
	v_mfma_f32_16x16x32_bf16 v[86:89], v[164:167], v[204:207], v[86:89]
	v_mfma_f32_16x16x32_bf16 v[78:81], v[156:159], v[212:215], v[78:81]
	v_mfma_f32_16x16x32_bf16 v[70:73], v[164:167], v[212:215], v[70:73]
	v_mfma_f32_16x16x32_bf16 v[122:125], v[168:171], v[184:187], v[122:125]
	v_mfma_f32_16x16x32_bf16 v[114:117], v[176:179], v[184:187], v[114:117]
	v_mfma_f32_16x16x32_bf16 v[106:109], v[168:171], v[192:195], v[106:109]
	v_mfma_f32_16x16x32_bf16 v[98:101], v[176:179], v[192:195], v[98:101]
	v_mfma_f32_16x16x32_bf16 v[90:93], v[168:171], v[200:203], v[90:93]
	v_mfma_f32_16x16x32_bf16 v[82:85], v[176:179], v[200:203], v[82:85]
	v_mfma_f32_16x16x32_bf16 v[74:77], v[168:171], v[208:211], v[74:77]
	v_mfma_f32_16x16x32_bf16 v[66:69], v[176:179], v[208:211], v[66:69]
	v_mfma_f32_16x16x32_bf16 v[122:125], v[172:175], v[188:191], v[122:125]
	v_mfma_f32_16x16x32_bf16 v[114:117], v[180:183], v[188:191], v[114:117]
	v_mfma_f32_16x16x32_bf16 v[106:109], v[172:175], v[196:199], v[106:109]
	v_mfma_f32_16x16x32_bf16 v[98:101], v[180:183], v[196:199], v[98:101]
	v_mfma_f32_16x16x32_bf16 v[90:93], v[172:175], v[204:207], v[90:93]
	v_mfma_f32_16x16x32_bf16 v[82:85], v[180:183], v[204:207], v[82:85]
	v_mfma_f32_16x16x32_bf16 v[74:77], v[172:175], v[212:215], v[74:77]
	v_mfma_f32_16x16x32_bf16 v[66:69], v[180:183], v[212:215], v[66:69]
	s_setprio 0
	s_barrier
	s_add_i32 s78, s78, s45
	s_mov_b32 m0, s78
	ds_read_b128 v[184:187], v147 offset:16384
	ds_read_b128 v[188:191], v147 offset:17408
	ds_read_b128 v[192:195], v147 offset:18432
	ds_read_b128 v[196:199], v147 offset:19456
	ds_read_b128 v[200:203], v147 offset:20480
	ds_read_b128 v[204:207], v147 offset:21504
	ds_read_b128 v[208:211], v147 offset:22528
	ds_read_b128 v[212:215], v147 offset:23552
	global_load_lds_dwordx4 v0, s[38:39]
	s_add_i32 m0, s78, 0x2000
	s_add_u32 s78, s38, 0x40000
	s_addc_u32 s79, s39, 0
	s_add_i32 s9, s9, s45
	global_load_lds_dwordx4 v134, s[38:39]
	s_mov_b32 m0, s9
	s_nop 0
	global_load_lds_dwordx4 v0, s[78:79]
	s_add_i32 m0, s9, 0x2000
	s_nop 0
	global_load_lds_dwordx4 v134, s[78:79]
	s_mov_b32 m0, s46
	s_nop 0
	global_load_lds_dwordx4 v130, vcc
	s_mov_b32 m0, s47
	s_nop 0
	global_load_lds_dwordx4 v132, vcc
	s_waitcnt vmcnt(8)
	s_waitcnt lgkmcnt(0)
	s_barrier
	s_setprio 1
	v_mfma_f32_16x16x32_bf16 v[62:65], v[140:143], v[184:187], v[62:65]
	v_mfma_f32_16x16x32_bf16 v[54:57], v[160:163], v[184:187], v[54:57]
	v_mfma_f32_16x16x32_bf16 v[46:49], v[140:143], v[192:195], v[46:49]
	v_mfma_f32_16x16x32_bf16 v[38:41], v[160:163], v[192:195], v[38:41]
	v_mfma_f32_16x16x32_bf16 v[30:33], v[140:143], v[200:203], v[30:33]
	v_mfma_f32_16x16x32_bf16 v[22:25], v[160:163], v[200:203], v[22:25]
	v_mfma_f32_16x16x32_bf16 v[14:17], v[140:143], v[208:211], v[14:17]
	v_mfma_f32_16x16x32_bf16 v[6:9], v[160:163], v[208:211], v[6:9]
	v_mfma_f32_16x16x32_bf16 v[62:65], v[156:159], v[188:191], v[62:65]
	v_mfma_f32_16x16x32_bf16 v[54:57], v[164:167], v[188:191], v[54:57]
	v_mfma_f32_16x16x32_bf16 v[46:49], v[156:159], v[196:199], v[46:49]
	v_mfma_f32_16x16x32_bf16 v[38:41], v[164:167], v[196:199], v[38:41]
	v_mfma_f32_16x16x32_bf16 v[30:33], v[156:159], v[204:207], v[30:33]
	v_mfma_f32_16x16x32_bf16 v[22:25], v[164:167], v[204:207], v[22:25]
	v_mfma_f32_16x16x32_bf16 v[14:17], v[156:159], v[212:215], v[14:17]
	v_mfma_f32_16x16x32_bf16 v[6:9], v[164:167], v[212:215], v[6:9]
	v_mfma_f32_16x16x32_bf16 v[58:61], v[168:171], v[184:187], v[58:61]
	v_mfma_f32_16x16x32_bf16 v[50:53], v[176:179], v[184:187], v[50:53]
	v_mfma_f32_16x16x32_bf16 v[42:45], v[168:171], v[192:195], v[42:45]
	v_mfma_f32_16x16x32_bf16 v[34:37], v[176:179], v[192:195], v[34:37]
	v_mfma_f32_16x16x32_bf16 v[26:29], v[168:171], v[200:203], v[26:29]
	v_mfma_f32_16x16x32_bf16 v[18:21], v[176:179], v[200:203], v[18:21]
	v_mfma_f32_16x16x32_bf16 v[10:13], v[168:171], v[208:211], v[10:13]
	v_mfma_f32_16x16x32_bf16 v[2:5], v[176:179], v[208:211], v[2:5]
	v_mfma_f32_16x16x32_bf16 v[58:61], v[172:175], v[188:191], v[58:61]
	v_mfma_f32_16x16x32_bf16 v[50:53], v[180:183], v[188:191], v[50:53]
	v_mfma_f32_16x16x32_bf16 v[42:45], v[172:175], v[196:199], v[42:45]
	v_mfma_f32_16x16x32_bf16 v[34:37], v[180:183], v[196:199], v[34:37]
	v_mfma_f32_16x16x32_bf16 v[26:29], v[172:175], v[204:207], v[26:29]
	v_mfma_f32_16x16x32_bf16 v[18:21], v[180:183], v[204:207], v[18:21]
	v_mfma_f32_16x16x32_bf16 v[10:13], v[172:175], v[212:215], v[10:13]
	v_mfma_f32_16x16x32_bf16 v[2:5], v[180:183], v[212:215], v[2:5]
	s_setprio 0
	s_barrier
	s_add_i32 s9, 0, 0x18000
	s_add_i32 s83, 0, 0x1c000
	v_add_u32_e32 v164, s9, v145
	v_add_u32_e32 v180, s83, v145
	ds_read_b128 v[140:143], v164
	ds_read_b128 v[156:159], v164 offset:1024
	ds_read_b128 v[160:163], v164 offset:2048
	ds_read_b128 v[164:167], v164 offset:3072
	ds_read_b128 v[168:171], v180
	ds_read_b128 v[172:175], v180 offset:1024
	ds_read_b128 v[176:179], v180 offset:2048
	ds_read_b128 v[180:183], v180 offset:3072
	s_add_u32 s78, vcc_lo, 0x40000
	s_addc_u32 s79, vcc_hi, 0
	s_mov_b32 m0, s48
	ds_read_b128 v[184:187], v147 offset:32768
	ds_read_b128 v[188:191], v147 offset:33792
	ds_read_b128 v[192:195], v147 offset:34816
	ds_read_b128 v[196:199], v147 offset:35840
	ds_read_b128 v[200:203], v147 offset:36864
	ds_read_b128 v[204:207], v147 offset:37888
	ds_read_b128 v[208:211], v147 offset:38912
	ds_read_b128 v[212:215], v147 offset:39936
	global_load_lds_dwordx4 v130, s[78:79]
	s_mov_b32 m0, s49
	s_nop 0
	global_load_lds_dwordx4 v132, s[78:79]
	s_waitcnt vmcnt(8)
	s_waitcnt lgkmcnt(0)
	s_barrier
	s_setprio 1
	v_mfma_f32_16x16x32_bf16 v[126:129], v[140:143], v[184:187], v[126:129]
	v_mfma_f32_16x16x32_bf16 v[118:121], v[160:163], v[184:187], v[118:121]
	v_mfma_f32_16x16x32_bf16 v[110:113], v[140:143], v[192:195], v[110:113]
	v_mfma_f32_16x16x32_bf16 v[102:105], v[160:163], v[192:195], v[102:105]
	v_mfma_f32_16x16x32_bf16 v[94:97], v[140:143], v[200:203], v[94:97]
	v_mfma_f32_16x16x32_bf16 v[86:89], v[160:163], v[200:203], v[86:89]
	v_mfma_f32_16x16x32_bf16 v[78:81], v[140:143], v[208:211], v[78:81]
	v_mfma_f32_16x16x32_bf16 v[70:73], v[160:163], v[208:211], v[70:73]
	v_mfma_f32_16x16x32_bf16 v[126:129], v[156:159], v[188:191], v[126:129]
	v_mfma_f32_16x16x32_bf16 v[118:121], v[164:167], v[188:191], v[118:121]
	v_mfma_f32_16x16x32_bf16 v[110:113], v[156:159], v[196:199], v[110:113]
	v_mfma_f32_16x16x32_bf16 v[102:105], v[164:167], v[196:199], v[102:105]
	v_mfma_f32_16x16x32_bf16 v[94:97], v[156:159], v[204:207], v[94:97]
	v_mfma_f32_16x16x32_bf16 v[86:89], v[164:167], v[204:207], v[86:89]
	v_mfma_f32_16x16x32_bf16 v[78:81], v[156:159], v[212:215], v[78:81]
	v_mfma_f32_16x16x32_bf16 v[70:73], v[164:167], v[212:215], v[70:73]
	v_mfma_f32_16x16x32_bf16 v[122:125], v[168:171], v[184:187], v[122:125]
	v_mfma_f32_16x16x32_bf16 v[114:117], v[176:179], v[184:187], v[114:117]
	v_mfma_f32_16x16x32_bf16 v[106:109], v[168:171], v[192:195], v[106:109]
	v_mfma_f32_16x16x32_bf16 v[98:101], v[176:179], v[192:195], v[98:101]
	v_mfma_f32_16x16x32_bf16 v[90:93], v[168:171], v[200:203], v[90:93]
	v_mfma_f32_16x16x32_bf16 v[82:85], v[176:179], v[200:203], v[82:85]
	v_mfma_f32_16x16x32_bf16 v[74:77], v[168:171], v[208:211], v[74:77]
	v_mfma_f32_16x16x32_bf16 v[66:69], v[176:179], v[208:211], v[66:69]
	v_mfma_f32_16x16x32_bf16 v[122:125], v[172:175], v[188:191], v[122:125]
	v_mfma_f32_16x16x32_bf16 v[114:117], v[180:183], v[188:191], v[114:117]
	v_mfma_f32_16x16x32_bf16 v[106:109], v[172:175], v[196:199], v[106:109]
	v_mfma_f32_16x16x32_bf16 v[98:101], v[180:183], v[196:199], v[98:101]
	v_mfma_f32_16x16x32_bf16 v[90:93], v[172:175], v[204:207], v[90:93]
	v_mfma_f32_16x16x32_bf16 v[82:85], v[180:183], v[204:207], v[82:85]
	v_mfma_f32_16x16x32_bf16 v[74:77], v[172:175], v[212:215], v[74:77]
	v_mfma_f32_16x16x32_bf16 v[66:69], v[180:183], v[212:215], v[66:69]
	s_setprio 0
	s_barrier
	s_add_i32 s9, s9, s45
	s_add_i32 m0, s9, 0xffffff80
	ds_read_b128 v[184:187], v147 offset:49152
	ds_read_b128 v[188:191], v147 offset:50176
	ds_read_b128 v[192:195], v147 offset:51200
	ds_read_b128 v[196:199], v147 offset:52224
	ds_read_b128 v[200:203], v147 offset:53248
	ds_read_b128 v[204:207], v147 offset:54272
	ds_read_b128 v[208:211], v147 offset:55296
	ds_read_b128 v[212:215], v147 offset:56320
	global_load_lds_dwordx4 v0, s[38:39] offset:128
	s_add_i32 m0, s9, 0x1f80
	s_add_i32 s9, s83, s45
	global_load_lds_dwordx4 v134, s[38:39] offset:128
	s_add_u32 s38, s38, 0x40080
	s_addc_u32 s39, s39, 0
	s_mov_b32 m0, s9
	s_nop 0
	global_load_lds_dwordx4 v0, s[38:39]
	s_add_i32 m0, s9, 0x2000
	s_nop 0
	global_load_lds_dwordx4 v134, s[38:39]
	s_add_i32 m0, s50, 0xffffff80
	s_nop 0
	global_load_lds_dwordx4 v130, vcc offset:128
	s_add_i32 m0, s51, 0xffffff80
	s_nop 0
	global_load_lds_dwordx4 v132, vcc offset:128
	s_waitcnt vmcnt(8)
	s_waitcnt lgkmcnt(0)
	s_barrier
	s_setprio 1
	v_mfma_f32_16x16x32_bf16 v[62:65], v[140:143], v[184:187], v[62:65]
	v_mfma_f32_16x16x32_bf16 v[54:57], v[160:163], v[184:187], v[54:57]
	v_mfma_f32_16x16x32_bf16 v[46:49], v[140:143], v[192:195], v[46:49]
	v_mfma_f32_16x16x32_bf16 v[38:41], v[160:163], v[192:195], v[38:41]
	v_mfma_f32_16x16x32_bf16 v[30:33], v[140:143], v[200:203], v[30:33]
	v_mfma_f32_16x16x32_bf16 v[22:25], v[160:163], v[200:203], v[22:25]
	v_mfma_f32_16x16x32_bf16 v[14:17], v[140:143], v[208:211], v[14:17]
	v_mfma_f32_16x16x32_bf16 v[6:9], v[160:163], v[208:211], v[6:9]
	v_mfma_f32_16x16x32_bf16 v[62:65], v[156:159], v[188:191], v[62:65]
	v_mfma_f32_16x16x32_bf16 v[54:57], v[164:167], v[188:191], v[54:57]
	v_mfma_f32_16x16x32_bf16 v[46:49], v[156:159], v[196:199], v[46:49]
	v_mfma_f32_16x16x32_bf16 v[38:41], v[164:167], v[196:199], v[38:41]
	v_mfma_f32_16x16x32_bf16 v[30:33], v[156:159], v[204:207], v[30:33]
	v_mfma_f32_16x16x32_bf16 v[22:25], v[164:167], v[204:207], v[22:25]
	v_mfma_f32_16x16x32_bf16 v[14:17], v[156:159], v[212:215], v[14:17]
	v_mfma_f32_16x16x32_bf16 v[6:9], v[164:167], v[212:215], v[6:9]
	v_mfma_f32_16x16x32_bf16 v[58:61], v[168:171], v[184:187], v[58:61]
	v_mfma_f32_16x16x32_bf16 v[50:53], v[176:179], v[184:187], v[50:53]
	v_mfma_f32_16x16x32_bf16 v[42:45], v[168:171], v[192:195], v[42:45]
	v_mfma_f32_16x16x32_bf16 v[34:37], v[176:179], v[192:195], v[34:37]
	v_mfma_f32_16x16x32_bf16 v[26:29], v[168:171], v[200:203], v[26:29]
	v_mfma_f32_16x16x32_bf16 v[18:21], v[176:179], v[200:203], v[18:21]
	v_mfma_f32_16x16x32_bf16 v[10:13], v[168:171], v[208:211], v[10:13]
	v_mfma_f32_16x16x32_bf16 v[2:5], v[176:179], v[208:211], v[2:5]
	v_mfma_f32_16x16x32_bf16 v[58:61], v[172:175], v[188:191], v[58:61]
	v_mfma_f32_16x16x32_bf16 v[50:53], v[180:183], v[188:191], v[50:53]
	v_mfma_f32_16x16x32_bf16 v[42:45], v[172:175], v[196:199], v[42:45]
	v_mfma_f32_16x16x32_bf16 v[34:37], v[180:183], v[196:199], v[34:37]
	v_mfma_f32_16x16x32_bf16 v[26:29], v[172:175], v[204:207], v[26:29]
	v_mfma_f32_16x16x32_bf16 v[18:21], v[180:183], v[204:207], v[18:21]
	v_mfma_f32_16x16x32_bf16 v[10:13], v[172:175], v[212:215], v[10:13]
	v_mfma_f32_16x16x32_bf16 v[2:5], v[180:183], v[212:215], v[2:5]
	s_setprio 0
	s_barrier
	s_add_i32 s75, s75, 2
	s_add_u32 s96, s96, 0x100
	s_addc_u32 s97, s97, 0
	s_add_u32 s53, s53, 0x100
	s_addc_u32 s61, s61, 0
	s_cmp_gt_u32 s75, 13
	s_cbranch_scc0 .LBB0_846
	s_and_b64 vcc, exec, s[14:15]
	s_cbranch_vccz .LBB0_849
	s_barrier
